# cache policy: plain store epilogue (conv u, retention v|g, context k|v) and the conv-gate's u loads non-temporal as well
# baseline (speedup 1.0000x reference)
; __device__ __forceinline__ unsigned cvt_pk_bf16(float lo, float hi) { unsigned r; asm volatile("v_cvt_pk_bf16_f32 %0, %1, %2" : "=v"(r) : "v"(lo), "v"(hi)); return r; }
; __device__ __forceinline__ float bflo(unsigned w) { return __uint_as_float(w << 16); }
; __device__ __forceinline__ float bfhi(unsigned w) { return __uint_as_float(w & 0xffff0000u); }
; __device__ __forceinline__ void convgate_phase(const bf16_t* U, bf16_t* H, int rows, const float* ck, int gw, int NGW, int lane) {
;     for (int row = gw; row < rows; row += NGW) {
;         const bool lat = row < ML; const int t = lat ? (row & (SEQ - 1)) : ((row - ML) & (CL - 1)); const int L = lat ? SEQ : CL;
;         const bool hasp = t > 0, hasn = t < L - 1;
;         const bf16_t* ur = U + (size_t)row * 3072;
;         u32x4 bq[2], cq[2], vq[2], cp[2], vp[2], cn[2], vn[2];
; #pragma unroll
;         for (int hf = 0; hf < 2; ++hf) {
;             const int c0 = lane * 16 + hf * 8;
;             bq[hf] = *(const u32x4*)(ur + c0); cq[hf] = *(const u32x4*)(ur + 1024 + c0); vq[hf] = *(const u32x4*)(ur + 2048 + c0);
;             cp[hf] = (u32x4){0, 0, 0, 0}; vp[hf] = cp[hf]; cn[hf] = cp[hf]; vn[hf] = cp[hf];
;             if (hasp) { cp[hf] = *(const u32x4*)(ur - 3072 + 1024 + c0); vp[hf] = *(const u32x4*)(ur - 3072 + 2048 + c0); }
;             if (hasn) { cn[hf] = *(const u32x4*)(ur + 3072 + 1024 + c0); vn[hf] = *(const u32x4*)(ur + 3072 + 2048 + c0); }
;         }
; #pragma unroll
;         for (int hf = 0; hf < 2; ++hf) {
;             const int c0 = lane * 16 + hf * 8;
;             u32x4 ow;
; #pragma unroll
;             for (int e = 0; e < 4; ++e) {
;                 const f32x2 w0 = *(const f32x2*)(ck + c0 + 2 * e), w1 = *(const f32x2*)(ck + D + c0 + 2 * e), w2 = *(const f32x2*)(ck + 2 * D + c0 + 2 * e);
;                 const float lo = bflo(bq[hf][e]) * (w0[0] * (bflo(cp[hf][e]) * bflo(vp[hf][e])) + w1[0] * (bflo(cq[hf][e]) * bflo(vq[hf][e])) + w2[0] * (bflo(cn[hf][e]) * bflo(vn[hf][e])));
;                 const float hi = bfhi(bq[hf][e]) * (w0[1] * (bfhi(cp[hf][e]) * bfhi(vp[hf][e])) + w1[1] * (bfhi(cq[hf][e]) * bfhi(vq[hf][e])) + w2[1] * (bfhi(cn[hf][e]) * bfhi(vn[hf][e])));
;                 ow[e] = cvt_pk_bf16(lo, hi);
.Lcg9_top:
	global_load_dwordx4 v[114:117], v1, s[4:5] offset:2048 nt
	global_load_dwordx4 v[118:121], v1, s[4:5] offset:2064 nt
	global_load_dwordx4 v[122:125], v2, s[4:5] nt
	global_load_dwordx4 v[126:129], v2, s[4:5] offset:16 nt
	s_add_u32 s4, s4, 0x1800
	s_addc_u32 s5, s5, 0
	global_load_dwordx4 v[130:133], v1, s[4:5] offset:2048 nt
	global_load_dwordx4 v[134:137], v1, s[4:5] offset:2064 nt
	global_load_dwordx4 v[138:141], v2, s[4:5] nt
	global_load_dwordx4 v[142:145], v2, s[4:5] offset:16 nt
	s_add_u32 s4, s4, 0x1800
	s_addc_u32 s5, s5, 0
	global_load_dwordx4 v[146:149], v1, s[6:7] nt
	global_load_dwordx4 v[150:153], v1, s[6:7] offset:16 nt
	s_add_u32 s6, s6, 0x1800
	s_addc_u32 s7, s7, 0
	global_load_dwordx4 v[160:163], v1, s[4:5] offset:2048 nt
	global_load_dwordx4 v[164:167], v1, s[4:5] offset:2064 nt
	global_load_dwordx4 v[168:171], v2, s[4:5] nt
	global_load_dwordx4 v[172:175], v2, s[4:5] offset:16 nt
	s_add_u32 s4, s4, 0x1800
	s_addc_u32 s5, s5, 0
	global_load_dwordx4 v[176:179], v1, s[6:7] nt
	global_load_dwordx4 v[180:183], v1, s[6:7] offset:16 nt
	s_add_u32 s6, s6, 0x1800
	s_addc_u32 s7, s7, 0
	s_waitcnt vmcnt(12)
	v_lshlrev_b32_e32 v202, 16, v114
	v_and_b32_e32 v203, s14, v114
	v_lshlrev_b32_e32 v204, 16, v122
	v_and_b32_e32 v205, s14, v122
	v_pk_mul_f32 v[52:53], v[202:203], v[204:205]
	v_lshlrev_b32_e32 v206, 16, v115
	v_and_b32_e32 v207, s14, v115
	v_lshlrev_b32_e32 v208, 16, v123
	v_and_b32_e32 v209, s14, v123
	v_pk_mul_f32 v[54:55], v[206:207], v[208:209]
	v_lshlrev_b32_e32 v210, 16, v116
	v_and_b32_e32 v211, s14, v116
	v_lshlrev_b32_e32 v212, 16, v124
	v_and_b32_e32 v213, s14, v124
	v_pk_mul_f32 v[56:57], v[210:211], v[212:213]
	v_lshlrev_b32_e32 v202, 16, v117
	v_and_b32_e32 v203, s14, v117
	v_lshlrev_b32_e32 v204, 16, v125
	v_and_b32_e32 v205, s14, v125
	v_pk_mul_f32 v[58:59], v[202:203], v[204:205]
	v_lshlrev_b32_e32 v206, 16, v118
	v_and_b32_e32 v207, s14, v118
	v_lshlrev_b32_e32 v208, 16, v126
	v_and_b32_e32 v209, s14, v126
	v_pk_mul_f32 v[60:61], v[206:207], v[208:209]
	v_lshlrev_b32_e32 v210, 16, v119
	v_and_b32_e32 v211, s14, v119
	v_lshlrev_b32_e32 v212, 16, v127
	v_and_b32_e32 v213, s14, v127
	v_pk_mul_f32 v[62:63], v[210:211], v[212:213]
	v_lshlrev_b32_e32 v202, 16, v120
	v_and_b32_e32 v203, s14, v120
	v_lshlrev_b32_e32 v204, 16, v128
	v_and_b32_e32 v205, s14, v128
	v_pk_mul_f32 v[64:65], v[202:203], v[204:205]
	v_lshlrev_b32_e32 v206, 16, v121
	v_and_b32_e32 v207, s14, v121
	v_lshlrev_b32_e32 v208, 16, v129
	v_and_b32_e32 v209, s14, v129
	v_pk_mul_f32 v[66:67], v[206:207], v[208:209]
	global_load_dwordx4 v[114:117], v1, s[4:5] offset:2048 nt
	global_load_dwordx4 v[118:121], v1, s[4:5] offset:2064 nt
	global_load_dwordx4 v[122:125], v2, s[4:5] nt
	global_load_dwordx4 v[126:129], v2, s[4:5] offset:16 nt
	s_add_u32 s4, s4, 0x1800
	s_addc_u32 s5, s5, 0
	global_load_dwordx4 v[226:229], v1, s[6:7] nt
	global_load_dwordx4 v[230:233], v1, s[6:7] offset:16 nt
	s_add_u32 s6, s6, 0x1800
	s_addc_u32 s7, s7, 0
	s_waitcnt vmcnt(14)
	v_lshlrev_b32_e32 v202, 16, v130
	v_and_b32_e32 v203, s14, v130
	v_lshlrev_b32_e32 v204, 16, v138
	v_and_b32_e32 v205, s14, v138
	v_pk_mul_f32 v[68:69], v[202:203], v[204:205]
	v_lshlrev_b32_e32 v206, 16, v131
	v_and_b32_e32 v207, s14, v131
	v_lshlrev_b32_e32 v208, 16, v139
	v_and_b32_e32 v209, s14, v139
	v_pk_mul_f32 v[70:71], v[206:207], v[208:209]
	v_lshlrev_b32_e32 v210, 16, v132
	v_and_b32_e32 v211, s14, v132
	v_lshlrev_b32_e32 v212, 16, v140
	v_and_b32_e32 v213, s14, v140
	v_pk_mul_f32 v[72:73], v[210:211], v[212:213]
	v_lshlrev_b32_e32 v202, 16, v133
	v_and_b32_e32 v203, s14, v133
	v_lshlrev_b32_e32 v204, 16, v141
	v_and_b32_e32 v205, s14, v141
	v_pk_mul_f32 v[74:75], v[202:203], v[204:205]
	v_lshlrev_b32_e32 v206, 16, v134
	v_and_b32_e32 v207, s14, v134
	v_lshlrev_b32_e32 v208, 16, v142
	v_and_b32_e32 v209, s14, v142
	v_pk_mul_f32 v[76:77], v[206:207], v[208:209]
	v_lshlrev_b32_e32 v210, 16, v135
	v_and_b32_e32 v211, s14, v135
	v_lshlrev_b32_e32 v212, 16, v143
	v_and_b32_e32 v213, s14, v143
	v_pk_mul_f32 v[78:79], v[210:211], v[212:213]
	v_lshlrev_b32_e32 v202, 16, v136
	v_and_b32_e32 v203, s14, v136
	v_lshlrev_b32_e32 v204, 16, v144
	v_and_b32_e32 v205, s14, v144
	v_pk_mul_f32 v[80:81], v[202:203], v[204:205]
	v_lshlrev_b32_e32 v206, 16, v137
	v_and_b32_e32 v207, s14, v137
	v_lshlrev_b32_e32 v208, 16, v145
	v_and_b32_e32 v209, s14, v145
	v_pk_mul_f32 v[82:83], v[206:207], v[208:209]
	global_load_dwordx4 v[130:133], v1, s[4:5] offset:2048 nt
	global_load_dwordx4 v[134:137], v1, s[4:5] offset:2064 nt
	global_load_dwordx4 v[138:141], v2, s[4:5] nt
	global_load_dwordx4 v[142:145], v2, s[4:5] offset:16 nt
	s_add_u32 s4, s4, 0x1800
	s_addc_u32 s5, s5, 0
	s_waitcnt vmcnt(12)
	v_lshlrev_b32_e32 v202, 16, v160
	v_and_b32_e32 v203, s14, v160
	v_lshlrev_b32_e32 v204, 16, v168
	v_and_b32_e32 v205, s14, v168
	v_pk_mul_f32 v[98:99], v[202:203], v[204:205]
	v_lshlrev_b32_e32 v206, 16, v161
	v_and_b32_e32 v207, s14, v161
	v_lshlrev_b32_e32 v208, 16, v169
	v_and_b32_e32 v209, s14, v169
	v_pk_mul_f32 v[100:101], v[206:207], v[208:209]
	v_lshlrev_b32_e32 v210, 16, v162
	v_and_b32_e32 v211, s14, v162
	v_lshlrev_b32_e32 v212, 16, v170
	v_and_b32_e32 v213, s14, v170
	v_pk_mul_f32 v[102:103], v[210:211], v[212:213]
	v_lshlrev_b32_e32 v202, 16, v163
	v_and_b32_e32 v203, s14, v163
	v_lshlrev_b32_e32 v204, 16, v171
	v_and_b32_e32 v205, s14, v171
	v_pk_mul_f32 v[104:105], v[202:203], v[204:205]
	v_lshlrev_b32_e32 v206, 16, v164
	v_and_b32_e32 v207, s14, v164
	v_lshlrev_b32_e32 v208, 16, v172
	v_and_b32_e32 v209, s14, v172
	v_pk_mul_f32 v[106:107], v[206:207], v[208:209]
	v_lshlrev_b32_e32 v210, 16, v165
	v_and_b32_e32 v211, s14, v165
	v_lshlrev_b32_e32 v212, 16, v173
	v_and_b32_e32 v213, s14, v173
	v_pk_mul_f32 v[108:109], v[210:211], v[212:213]
	v_lshlrev_b32_e32 v202, 16, v166
	v_and_b32_e32 v203, s14, v166
	v_lshlrev_b32_e32 v204, 16, v174
	v_and_b32_e32 v205, s14, v174
	v_pk_mul_f32 v[110:111], v[202:203], v[204:205]
	v_lshlrev_b32_e32 v206, 16, v167
	v_and_b32_e32 v207, s14, v167
	v_lshlrev_b32_e32 v208, 16, v175
	v_and_b32_e32 v209, s14, v175
	v_pk_mul_f32 v[112:113], v[206:207], v[208:209]
	global_load_dwordx4 v[160:163], v1, s[4:5] offset:2048 nt
	global_load_dwordx4 v[164:167], v1, s[4:5] offset:2064 nt
	global_load_dwordx4 v[168:171], v2, s[4:5] nt
	global_load_dwordx4 v[172:175], v2, s[4:5] offset:16 nt
	s_add_u32 s4, s4, 0x1800
	s_addc_u32 s5, s5, 0
	s_add_i32 s12, s11, 0
	s_cmp_lt_u32 s12, 0x4000
	s_cselect_b32 s29, s3, s13
	s_and_b32 s27, s12, s29
	v_pk_mul_f32 v[234:235], v[20:21], v[68:69]
	v_pk_mul_f32 v[236:237], v[22:23], v[70:71]
	v_pk_mul_f32 v[238:239], v[24:25], v[72:73]
	v_pk_mul_f32 v[240:241], v[26:27], v[74:75]
	v_pk_mul_f32 v[242:243], v[28:29], v[76:77]
	v_pk_mul_f32 v[244:245], v[30:31], v[78:79]
	v_pk_mul_f32 v[246:247], v[32:33], v[80:81]
	v_pk_mul_f32 v[248:249], v[34:35], v[82:83]
	s_cmp_eq_u32 s27, 0
	s_cbranch_scc1 .Lcg9_np0
; __device__ __forceinline__ float bflo(unsigned w) { return __uint_as_float(w << 16); }
; __device__ __forceinline__ float bfhi(unsigned w) { return __uint_as_float(w & 0xffff0000u); }
; __device__ __forceinline__ void convgate_phase(const bf16_t* U, bf16_t* H, int rows, const float* ck, int gw, int NGW, int lane) {
;     ...
;                 const float lo = bflo(bq[hf][e]) * (w0[0] * (bflo(cp[hf][e]) * bflo(vp[hf][e])) + w1[0] * (bflo(cq[hf][e]) * bflo(vq[hf][e])) + w2[0] * (bflo(cn[hf][e]) * bflo(vn[hf][e])));
;                 const float hi = bfhi(bq[hf][e]) * (w0[1] * (bfhi(cp[hf][e]) * bfhi(vp[hf][e])) + w1[1] * (bfhi(cq[hf][e]) * bfhi(vq[hf][e])) + w2[1] * (bfhi(cn[hf][e]) * bfhi(vn[hf][e])));
	v_pk_fma_f32 v[234:235], v[4:5], v[52:53], v[234:235]
	v_pk_fma_f32 v[236:237], v[6:7], v[54:55], v[236:237]
	v_pk_fma_f32 v[238:239], v[8:9], v[56:57], v[238:239]
	v_pk_fma_f32 v[240:241], v[10:11], v[58:59], v[240:241]
	v_pk_fma_f32 v[242:243], v[12:13], v[60:61], v[242:243]
	v_pk_fma_f32 v[244:245], v[14:15], v[62:63], v[244:245]
	v_pk_fma_f32 v[246:247], v[16:17], v[64:65], v[246:247]
	v_pk_fma_f32 v[248:249], v[18:19], v[66:67], v[248:249]

; __device__ __forceinline__ unsigned cvt_pk_bf16(float lo, float hi) { unsigned r; asm volatile("v_cvt_pk_bf16_f32 %0, %1, %2" : "=v"(r) : "v"(lo), "v"(hi)); return r; }
; __device__ __forceinline__ float bflo(unsigned w) { return __uint_as_float(w << 16); }
; __device__ __forceinline__ float bfhi(unsigned w) { return __uint_as_float(w & 0xffff0000u); }
; __device__ __forceinline__ void convgate_phase(const bf16_t* U, bf16_t* H, int rows, const float* ck, int gw, int NGW, int lane) {
;     ...
;                 const float lo = bflo(bq[hf][e]) * (w0[0] * (bflo(cp[hf][e]) * bflo(vp[hf][e])) + w1[0] * (bflo(cq[hf][e]) * bflo(vq[hf][e])) + w2[0] * (bflo(cn[hf][e]) * bflo(vn[hf][e])));
;                 const float hi = bfhi(bq[hf][e]) * (w0[1] * (bfhi(cp[hf][e]) * bfhi(vp[hf][e])) + w1[1] * (bfhi(cq[hf][e]) * bfhi(vq[hf][e])) + w2[1] * (bfhi(cn[hf][e]) * bfhi(vn[hf][e])));
;                 ow[e] = cvt_pk_bf16(lo, hi);
;             }
;             *(u32x4*)(H + (size_t)row * D + c0) = ow;
;         }
.Lcg9_nn0:
	v_lshlrev_b32_e32 v202, 16, v146
	v_and_b32_e32 v203, s14, v146
	v_pk_mul_f32 v[234:235], v[234:235], v[202:203]
	v_lshlrev_b32_e32 v206, 16, v147
	v_and_b32_e32 v207, s14, v147
	v_pk_mul_f32 v[236:237], v[236:237], v[206:207]
	v_lshlrev_b32_e32 v210, 16, v148
	v_and_b32_e32 v211, s14, v148
	v_pk_mul_f32 v[238:239], v[238:239], v[210:211]
	v_lshlrev_b32_e32 v202, 16, v149
	v_and_b32_e32 v203, s14, v149
	v_pk_mul_f32 v[240:241], v[240:241], v[202:203]
	v_lshlrev_b32_e32 v206, 16, v150
	v_and_b32_e32 v207, s14, v150
	v_pk_mul_f32 v[242:243], v[242:243], v[206:207]
	v_lshlrev_b32_e32 v210, 16, v151
	v_and_b32_e32 v211, s14, v151
	v_pk_mul_f32 v[244:245], v[244:245], v[210:211]
	v_lshlrev_b32_e32 v202, 16, v152
	v_and_b32_e32 v203, s14, v152
	v_pk_mul_f32 v[246:247], v[246:247], v[202:203]
	v_lshlrev_b32_e32 v206, 16, v153
	v_and_b32_e32 v207, s14, v153
	v_pk_mul_f32 v[248:249], v[248:249], v[206:207]
	v_cvt_pk_bf16_f32 v84, v234, v235
	v_cvt_pk_bf16_f32 v85, v236, v237
	v_cvt_pk_bf16_f32 v86, v238, v239
	v_cvt_pk_bf16_f32 v87, v240, v241
	v_cvt_pk_bf16_f32 v88, v242, v243
	v_cvt_pk_bf16_f32 v89, v244, v245
	v_cvt_pk_bf16_f32 v90, v246, v247
	v_cvt_pk_bf16_f32 v91, v248, v249
	global_store_dwordx4 v1, v[84:87], s[8:9]
	global_store_dwordx4 v1, v[88:91], s[8:9] offset:16
	s_add_u32 s8, s8, 0x800
	s_addc_u32 s9, s9, 0
	global_load_dwordx4 v[146:149], v1, s[6:7] nt
	global_load_dwordx4 v[150:153], v1, s[6:7] offset:16 nt
	s_add_u32 s6, s6, 0x1800
	s_addc_u32 s7, s7, 0
	s_waitcnt vmcnt(14)
	v_lshlrev_b32_e32 v202, 16, v114
	v_and_b32_e32 v203, s14, v114
	v_lshlrev_b32_e32 v204, 16, v122
	v_and_b32_e32 v205, s14, v122
	v_pk_mul_f32 v[52:53], v[202:203], v[204:205]
	v_lshlrev_b32_e32 v206, 16, v115
	v_and_b32_e32 v207, s14, v115
	v_lshlrev_b32_e32 v208, 16, v123
	v_and_b32_e32 v209, s14, v123
	v_pk_mul_f32 v[54:55], v[206:207], v[208:209]
	v_lshlrev_b32_e32 v210, 16, v116
	v_and_b32_e32 v211, s14, v116
	v_lshlrev_b32_e32 v212, 16, v124
	v_and_b32_e32 v213, s14, v124
	v_pk_mul_f32 v[56:57], v[210:211], v[212:213]
	v_lshlrev_b32_e32 v202, 16, v117
	v_and_b32_e32 v203, s14, v117
	v_lshlrev_b32_e32 v204, 16, v125
	v_and_b32_e32 v205, s14, v125
	v_pk_mul_f32 v[58:59], v[202:203], v[204:205]
	v_lshlrev_b32_e32 v206, 16, v118
	v_and_b32_e32 v207, s14, v118
	v_lshlrev_b32_e32 v208, 16, v126
	v_and_b32_e32 v209, s14, v126
	v_pk_mul_f32 v[60:61], v[206:207], v[208:209]
	v_lshlrev_b32_e32 v210, 16, v119
	v_and_b32_e32 v211, s14, v119
	v_lshlrev_b32_e32 v212, 16, v127
	v_and_b32_e32 v213, s14, v127
	v_pk_mul_f32 v[62:63], v[210:211], v[212:213]
	v_lshlrev_b32_e32 v202, 16, v120
	v_and_b32_e32 v203, s14, v120
	v_lshlrev_b32_e32 v204, 16, v128
	v_and_b32_e32 v205, s14, v128
	v_pk_mul_f32 v[64:65], v[202:203], v[204:205]
	v_lshlrev_b32_e32 v206, 16, v121
	v_and_b32_e32 v207, s14, v121
	v_lshlrev_b32_e32 v208, 16, v129
	v_and_b32_e32 v209, s14, v129
	v_pk_mul_f32 v[66:67], v[206:207], v[208:209]
	global_load_dwordx4 v[114:117], v1, s[4:5] offset:2048 nt
	global_load_dwordx4 v[118:121], v1, s[4:5] offset:2064 nt
	global_load_dwordx4 v[122:125], v2, s[4:5] nt
	global_load_dwordx4 v[126:129], v2, s[4:5] offset:16 nt
	s_add_u32 s4, s4, 0x1800
	s_addc_u32 s5, s5, 0
	s_add_i32 s12, s11, 1
	s_cmp_lt_u32 s12, 0x4000
	s_cselect_b32 s29, s3, s13
	s_and_b32 s27, s12, s29
	v_pk_mul_f32 v[234:235], v[20:21], v[98:99]
	v_pk_mul_f32 v[236:237], v[22:23], v[100:101]
	v_pk_mul_f32 v[238:239], v[24:25], v[102:103]
	v_pk_mul_f32 v[240:241], v[26:27], v[104:105]
	v_pk_mul_f32 v[242:243], v[28:29], v[106:107]
	v_pk_mul_f32 v[244:245], v[30:31], v[108:109]
	v_pk_mul_f32 v[246:247], v[32:33], v[110:111]
	v_pk_mul_f32 v[248:249], v[34:35], v[112:113]
	s_cmp_eq_u32 s27, 0
	s_cbranch_scc1 .Lcg9_np1
	v_pk_fma_f32 v[234:235], v[4:5], v[68:69], v[234:235]
	v_pk_fma_f32 v[236:237], v[6:7], v[70:71], v[236:237]
	v_pk_fma_f32 v[238:239], v[8:9], v[72:73], v[238:239]
	v_pk_fma_f32 v[240:241], v[10:11], v[74:75], v[240:241]
	v_pk_fma_f32 v[242:243], v[12:13], v[76:77], v[242:243]
	v_pk_fma_f32 v[244:245], v[14:15], v[78:79], v[244:245]
	v_pk_fma_f32 v[246:247], v[16:17], v[80:81], v[246:247]
	v_pk_fma_f32 v[248:249], v[18:19], v[82:83], v[248:249]

; __device__ __forceinline__ unsigned cvt_pk_bf16(float lo, float hi) { unsigned r; asm volatile("v_cvt_pk_bf16_f32 %0, %1, %2" : "=v"(r) : "v"(lo), "v"(hi)); return r; }
; __device__ __forceinline__ float bflo(unsigned w) { return __uint_as_float(w << 16); }
; __device__ __forceinline__ float bfhi(unsigned w) { return __uint_as_float(w & 0xffff0000u); }
; __device__ __forceinline__ void convgate_phase(const bf16_t* U, bf16_t* H, int rows, const float* ck, int gw, int NGW, int lane) {
;     ...
;                 const float lo = bflo(bq[hf][e]) * (w0[0] * (bflo(cp[hf][e]) * bflo(vp[hf][e])) + w1[0] * (bflo(cq[hf][e]) * bflo(vq[hf][e])) + w2[0] * (bflo(cn[hf][e]) * bflo(vn[hf][e])));
;                 const float hi = bfhi(bq[hf][e]) * (w0[1] * (bfhi(cp[hf][e]) * bfhi(vp[hf][e])) + w1[1] * (bfhi(cq[hf][e]) * bfhi(vq[hf][e])) + w2[1] * (bfhi(cn[hf][e]) * bfhi(vn[hf][e])));
;                 ow[e] = cvt_pk_bf16(lo, hi);
;             }
;             *(u32x4*)(H + (size_t)row * D + c0) = ow;
;         }
.Lcg9_nn1:
	v_lshlrev_b32_e32 v202, 16, v176
	v_and_b32_e32 v203, s14, v176
	v_pk_mul_f32 v[234:235], v[234:235], v[202:203]
	v_lshlrev_b32_e32 v206, 16, v177
	v_and_b32_e32 v207, s14, v177
	v_pk_mul_f32 v[236:237], v[236:237], v[206:207]
	v_lshlrev_b32_e32 v210, 16, v178
	v_and_b32_e32 v211, s14, v178
	v_pk_mul_f32 v[238:239], v[238:239], v[210:211]
	v_lshlrev_b32_e32 v202, 16, v179
	v_and_b32_e32 v203, s14, v179
	v_pk_mul_f32 v[240:241], v[240:241], v[202:203]
	v_lshlrev_b32_e32 v206, 16, v180
	v_and_b32_e32 v207, s14, v180
	v_pk_mul_f32 v[242:243], v[242:243], v[206:207]
	v_lshlrev_b32_e32 v210, 16, v181
	v_and_b32_e32 v211, s14, v181
	v_pk_mul_f32 v[244:245], v[244:245], v[210:211]
	v_lshlrev_b32_e32 v202, 16, v182
	v_and_b32_e32 v203, s14, v182
	v_pk_mul_f32 v[246:247], v[246:247], v[202:203]
	v_lshlrev_b32_e32 v206, 16, v183
	v_and_b32_e32 v207, s14, v183
	v_pk_mul_f32 v[248:249], v[248:249], v[206:207]
	v_cvt_pk_bf16_f32 v84, v234, v235
	v_cvt_pk_bf16_f32 v85, v236, v237
	v_cvt_pk_bf16_f32 v86, v238, v239
	v_cvt_pk_bf16_f32 v87, v240, v241
	v_cvt_pk_bf16_f32 v88, v242, v243
	v_cvt_pk_bf16_f32 v89, v244, v245
	v_cvt_pk_bf16_f32 v90, v246, v247
	v_cvt_pk_bf16_f32 v91, v248, v249
	global_store_dwordx4 v1, v[84:87], s[8:9]
	global_store_dwordx4 v1, v[88:91], s[8:9] offset:16
	s_add_u32 s8, s8, 0x800
	s_addc_u32 s9, s9, 0
	global_load_dwordx4 v[176:179], v1, s[6:7] nt
	global_load_dwordx4 v[180:183], v1, s[6:7] offset:16 nt
	s_add_u32 s6, s6, 0x1800
	s_addc_u32 s7, s7, 0
	s_waitcnt vmcnt(16)
	v_lshlrev_b32_e32 v202, 16, v130
	v_and_b32_e32 v203, s14, v130
	v_lshlrev_b32_e32 v204, 16, v138
	v_and_b32_e32 v205, s14, v138
	v_pk_mul_f32 v[68:69], v[202:203], v[204:205]
	v_lshlrev_b32_e32 v206, 16, v131
	v_and_b32_e32 v207, s14, v131
	v_lshlrev_b32_e32 v208, 16, v139
	v_and_b32_e32 v209, s14, v139
	v_pk_mul_f32 v[70:71], v[206:207], v[208:209]
	v_lshlrev_b32_e32 v210, 16, v132
	v_and_b32_e32 v211, s14, v132
	v_lshlrev_b32_e32 v212, 16, v140
	v_and_b32_e32 v213, s14, v140
	v_pk_mul_f32 v[72:73], v[210:211], v[212:213]
	v_lshlrev_b32_e32 v202, 16, v133
	v_and_b32_e32 v203, s14, v133
	v_lshlrev_b32_e32 v204, 16, v141
	v_and_b32_e32 v205, s14, v141
	v_pk_mul_f32 v[74:75], v[202:203], v[204:205]
	v_lshlrev_b32_e32 v206, 16, v134
	v_and_b32_e32 v207, s14, v134
	v_lshlrev_b32_e32 v208, 16, v142
	v_and_b32_e32 v209, s14, v142
	v_pk_mul_f32 v[76:77], v[206:207], v[208:209]
	v_lshlrev_b32_e32 v210, 16, v135
	v_and_b32_e32 v211, s14, v135
	v_lshlrev_b32_e32 v212, 16, v143
	v_and_b32_e32 v213, s14, v143
	v_pk_mul_f32 v[78:79], v[210:211], v[212:213]
	v_lshlrev_b32_e32 v202, 16, v136
	v_and_b32_e32 v203, s14, v136
	v_lshlrev_b32_e32 v204, 16, v144
	v_and_b32_e32 v205, s14, v144
	v_pk_mul_f32 v[80:81], v[202:203], v[204:205]
	v_lshlrev_b32_e32 v206, 16, v137
	v_and_b32_e32 v207, s14, v137
	v_lshlrev_b32_e32 v208, 16, v145
	v_and_b32_e32 v209, s14, v145
	v_pk_mul_f32 v[82:83], v[206:207], v[208:209]
	global_load_dwordx4 v[130:133], v1, s[4:5] offset:2048 nt
	global_load_dwordx4 v[134:137], v1, s[4:5] offset:2064 nt
	global_load_dwordx4 v[138:141], v2, s[4:5] nt
	global_load_dwordx4 v[142:145], v2, s[4:5] offset:16 nt
	s_add_u32 s4, s4, 0x1800
	s_addc_u32 s5, s5, 0
	s_add_i32 s12, s11, 2
	s_cmp_lt_u32 s12, 0x4000
	s_cselect_b32 s29, s3, s13
	s_and_b32 s27, s12, s29
	v_pk_mul_f32 v[234:235], v[20:21], v[52:53]
	v_pk_mul_f32 v[236:237], v[22:23], v[54:55]
	v_pk_mul_f32 v[238:239], v[24:25], v[56:57]
	v_pk_mul_f32 v[240:241], v[26:27], v[58:59]
	v_pk_mul_f32 v[242:243], v[28:29], v[60:61]
	v_pk_mul_f32 v[244:245], v[30:31], v[62:63]
	v_pk_mul_f32 v[246:247], v[32:33], v[64:65]
	v_pk_mul_f32 v[248:249], v[34:35], v[66:67]
	s_cmp_eq_u32 s27, 0
	s_cbranch_scc1 .Lcg9_np2
	v_pk_fma_f32 v[234:235], v[4:5], v[98:99], v[234:235]
	v_pk_fma_f32 v[236:237], v[6:7], v[100:101], v[236:237]
	v_pk_fma_f32 v[238:239], v[8:9], v[102:103], v[238:239]
	v_pk_fma_f32 v[240:241], v[10:11], v[104:105], v[240:241]
	v_pk_fma_f32 v[242:243], v[12:13], v[106:107], v[242:243]
	v_pk_fma_f32 v[244:245], v[14:15], v[108:109], v[244:245]
	v_pk_fma_f32 v[246:247], v[16:17], v[110:111], v[246:247]
	v_pk_fma_f32 v[248:249], v[18:19], v[112:113], v[248:249]

; __device__ __forceinline__ unsigned cvt_pk_bf16(float lo, float hi) { unsigned r; asm volatile("v_cvt_pk_bf16_f32 %0, %1, %2" : "=v"(r) : "v"(lo), "v"(hi)); return r; }
; __device__ __forceinline__ float bflo(unsigned w) { return __uint_as_float(w << 16); }
; __device__ __forceinline__ float bfhi(unsigned w) { return __uint_as_float(w & 0xffff0000u); }
; __device__ __forceinline__ void convgate_phase(const bf16_t* U, bf16_t* H, int rows, const float* ck, int gw, int NGW, int lane) {
;     ...
;                 const float lo = bflo(bq[hf][e]) * (w0[0] * (bflo(cp[hf][e]) * bflo(vp[hf][e])) + w1[0] * (bflo(cq[hf][e]) * bflo(vq[hf][e])) + w2[0] * (bflo(cn[hf][e]) * bflo(vn[hf][e])));
;                 const float hi = bfhi(bq[hf][e]) * (w0[1] * (bfhi(cp[hf][e]) * bfhi(vp[hf][e])) + w1[1] * (bfhi(cq[hf][e]) * bfhi(vq[hf][e])) + w2[1] * (bfhi(cn[hf][e]) * bfhi(vn[hf][e])));
;                 ow[e] = cvt_pk_bf16(lo, hi);
;             }
;             *(u32x4*)(H + (size_t)row * D + c0) = ow;
;         }
.Lcg9_nn2:
	v_lshlrev_b32_e32 v202, 16, v226
	v_and_b32_e32 v203, s14, v226
	v_pk_mul_f32 v[234:235], v[234:235], v[202:203]
	v_lshlrev_b32_e32 v206, 16, v227
	v_and_b32_e32 v207, s14, v227
	v_pk_mul_f32 v[236:237], v[236:237], v[206:207]
	v_lshlrev_b32_e32 v210, 16, v228
	v_and_b32_e32 v211, s14, v228
	v_pk_mul_f32 v[238:239], v[238:239], v[210:211]
	v_lshlrev_b32_e32 v202, 16, v229
	v_and_b32_e32 v203, s14, v229
	v_pk_mul_f32 v[240:241], v[240:241], v[202:203]
	v_lshlrev_b32_e32 v206, 16, v230
	v_and_b32_e32 v207, s14, v230
	v_pk_mul_f32 v[242:243], v[242:243], v[206:207]
	v_lshlrev_b32_e32 v210, 16, v231
	v_and_b32_e32 v211, s14, v231
	v_pk_mul_f32 v[244:245], v[244:245], v[210:211]
	v_lshlrev_b32_e32 v202, 16, v232
	v_and_b32_e32 v203, s14, v232
	v_pk_mul_f32 v[246:247], v[246:247], v[202:203]
	v_lshlrev_b32_e32 v206, 16, v233
	v_and_b32_e32 v207, s14, v233
	v_pk_mul_f32 v[248:249], v[248:249], v[206:207]
	v_cvt_pk_bf16_f32 v84, v234, v235
	v_cvt_pk_bf16_f32 v85, v236, v237
	v_cvt_pk_bf16_f32 v86, v238, v239
	v_cvt_pk_bf16_f32 v87, v240, v241
	v_cvt_pk_bf16_f32 v88, v242, v243
	v_cvt_pk_bf16_f32 v89, v244, v245
	v_cvt_pk_bf16_f32 v90, v246, v247
	v_cvt_pk_bf16_f32 v91, v248, v249
	global_store_dwordx4 v1, v[84:87], s[8:9]
	global_store_dwordx4 v1, v[88:91], s[8:9] offset:16
	s_add_u32 s8, s8, 0x800
	s_addc_u32 s9, s9, 0
	global_load_dwordx4 v[226:229], v1, s[6:7] nt
	global_load_dwordx4 v[230:233], v1, s[6:7] offset:16 nt
	s_add_u32 s6, s6, 0x1800
	s_addc_u32 s7, s7, 0
	s_waitcnt vmcnt(16)
	v_lshlrev_b32_e32 v202, 16, v160
	v_and_b32_e32 v203, s14, v160
	v_lshlrev_b32_e32 v204, 16, v168
	v_and_b32_e32 v205, s14, v168
	v_pk_mul_f32 v[98:99], v[202:203], v[204:205]
	v_lshlrev_b32_e32 v206, 16, v161
	v_and_b32_e32 v207, s14, v161
	v_lshlrev_b32_e32 v208, 16, v169
	v_and_b32_e32 v209, s14, v169
	v_pk_mul_f32 v[100:101], v[206:207], v[208:209]
	v_lshlrev_b32_e32 v210, 16, v162
	v_and_b32_e32 v211, s14, v162
	v_lshlrev_b32_e32 v212, 16, v170
	v_and_b32_e32 v213, s14, v170
	v_pk_mul_f32 v[102:103], v[210:211], v[212:213]
	v_lshlrev_b32_e32 v202, 16, v163
	v_and_b32_e32 v203, s14, v163
	v_lshlrev_b32_e32 v204, 16, v171
	v_and_b32_e32 v205, s14, v171
	v_pk_mul_f32 v[104:105], v[202:203], v[204:205]
	v_lshlrev_b32_e32 v206, 16, v164
	v_and_b32_e32 v207, s14, v164
	v_lshlrev_b32_e32 v208, 16, v172
	v_and_b32_e32 v209, s14, v172
	v_pk_mul_f32 v[106:107], v[206:207], v[208:209]
	v_lshlrev_b32_e32 v210, 16, v165
	v_and_b32_e32 v211, s14, v165
	v_lshlrev_b32_e32 v212, 16, v173
	v_and_b32_e32 v213, s14, v173
	v_pk_mul_f32 v[108:109], v[210:211], v[212:213]
	v_lshlrev_b32_e32 v202, 16, v166
	v_and_b32_e32 v203, s14, v166
	v_lshlrev_b32_e32 v204, 16, v174
	v_and_b32_e32 v205, s14, v174
	v_pk_mul_f32 v[110:111], v[202:203], v[204:205]
	v_lshlrev_b32_e32 v206, 16, v167
	v_and_b32_e32 v207, s14, v167
	v_lshlrev_b32_e32 v208, 16, v175
	v_and_b32_e32 v209, s14, v175
	v_pk_mul_f32 v[112:113], v[206:207], v[208:209]
	global_load_dwordx4 v[160:163], v1, s[4:5] offset:2048 nt
	global_load_dwordx4 v[164:167], v1, s[4:5] offset:2064 nt
	global_load_dwordx4 v[168:171], v2, s[4:5] nt
	global_load_dwordx4 v[172:175], v2, s[4:5] offset:16 nt
	s_add_u32 s4, s4, 0x1800
	s_addc_u32 s5, s5, 0
	s_add_i32 s12, s11, 3
	s_cmp_lt_u32 s12, 0x4000
	s_cselect_b32 s29, s3, s13
	s_and_b32 s27, s12, s29
	v_pk_mul_f32 v[234:235], v[20:21], v[68:69]
	v_pk_mul_f32 v[236:237], v[22:23], v[70:71]
	v_pk_mul_f32 v[238:239], v[24:25], v[72:73]
	v_pk_mul_f32 v[240:241], v[26:27], v[74:75]
	v_pk_mul_f32 v[242:243], v[28:29], v[76:77]
	v_pk_mul_f32 v[244:245], v[30:31], v[78:79]
	v_pk_mul_f32 v[246:247], v[32:33], v[80:81]
	v_pk_mul_f32 v[248:249], v[34:35], v[82:83]
	s_cmp_eq_u32 s27, 0
	s_cbranch_scc1 .Lcg9_np3
	v_pk_fma_f32 v[234:235], v[4:5], v[52:53], v[234:235]
	v_pk_fma_f32 v[236:237], v[6:7], v[54:55], v[236:237]
	v_pk_fma_f32 v[238:239], v[8:9], v[56:57], v[238:239]
	v_pk_fma_f32 v[240:241], v[10:11], v[58:59], v[240:241]
	v_pk_fma_f32 v[242:243], v[12:13], v[60:61], v[242:243]
	v_pk_fma_f32 v[244:245], v[14:15], v[62:63], v[244:245]
	v_pk_fma_f32 v[246:247], v[16:17], v[64:65], v[246:247]
	v_pk_fma_f32 v[248:249], v[18:19], v[66:67], v[248:249]

; __device__ __forceinline__ unsigned cvt_pk_bf16(float lo, float hi) { unsigned r; asm volatile("v_cvt_pk_bf16_f32 %0, %1, %2" : "=v"(r) : "v"(lo), "v"(hi)); return r; }
; __device__ __forceinline__ float bflo(unsigned w) { return __uint_as_float(w << 16); }
; __device__ __forceinline__ float bfhi(unsigned w) { return __uint_as_float(w & 0xffff0000u); }
; __device__ __forceinline__ void convgate_phase(const bf16_t* U, bf16_t* H, int rows, const float* ck, int gw, int NGW, int lane) {
;     ...
;                 const float lo = bflo(bq[hf][e]) * (w0[0] * (bflo(cp[hf][e]) * bflo(vp[hf][e])) + w1[0] * (bflo(cq[hf][e]) * bflo(vq[hf][e])) + w2[0] * (bflo(cn[hf][e]) * bflo(vn[hf][e])));
;                 const float hi = bfhi(bq[hf][e]) * (w0[1] * (bfhi(cp[hf][e]) * bfhi(vp[hf][e])) + w1[1] * (bfhi(cq[hf][e]) * bfhi(vq[hf][e])) + w2[1] * (bfhi(cn[hf][e]) * bfhi(vn[hf][e])));
;                 ow[e] = cvt_pk_bf16(lo, hi);
;             }
;             *(u32x4*)(H + (size_t)row * D + c0) = ow;
;         }
.Lcg9_nn3:
	v_lshlrev_b32_e32 v202, 16, v146
	v_and_b32_e32 v203, s14, v146
	v_pk_mul_f32 v[234:235], v[234:235], v[202:203]
	v_lshlrev_b32_e32 v206, 16, v147
	v_and_b32_e32 v207, s14, v147
	v_pk_mul_f32 v[236:237], v[236:237], v[206:207]
	v_lshlrev_b32_e32 v210, 16, v148
	v_and_b32_e32 v211, s14, v148
	v_pk_mul_f32 v[238:239], v[238:239], v[210:211]
	v_lshlrev_b32_e32 v202, 16, v149
	v_and_b32_e32 v203, s14, v149
	v_pk_mul_f32 v[240:241], v[240:241], v[202:203]
	v_lshlrev_b32_e32 v206, 16, v150
	v_and_b32_e32 v207, s14, v150
	v_pk_mul_f32 v[242:243], v[242:243], v[206:207]
	v_lshlrev_b32_e32 v210, 16, v151
	v_and_b32_e32 v211, s14, v151
	v_pk_mul_f32 v[244:245], v[244:245], v[210:211]
	v_lshlrev_b32_e32 v202, 16, v152
	v_and_b32_e32 v203, s14, v152
	v_pk_mul_f32 v[246:247], v[246:247], v[202:203]
	v_lshlrev_b32_e32 v206, 16, v153
	v_and_b32_e32 v207, s14, v153
	v_pk_mul_f32 v[248:249], v[248:249], v[206:207]
	v_cvt_pk_bf16_f32 v84, v234, v235
	v_cvt_pk_bf16_f32 v85, v236, v237
	v_cvt_pk_bf16_f32 v86, v238, v239
	v_cvt_pk_bf16_f32 v87, v240, v241
	v_cvt_pk_bf16_f32 v88, v242, v243
	v_cvt_pk_bf16_f32 v89, v244, v245
	v_cvt_pk_bf16_f32 v90, v246, v247
	v_cvt_pk_bf16_f32 v91, v248, v249
	global_store_dwordx4 v1, v[84:87], s[8:9]
	global_store_dwordx4 v1, v[88:91], s[8:9] offset:16
	s_add_u32 s8, s8, 0x800
	s_addc_u32 s9, s9, 0
	global_load_dwordx4 v[146:149], v1, s[6:7] nt
	global_load_dwordx4 v[150:153], v1, s[6:7] offset:16 nt
	s_add_u32 s6, s6, 0x1800
	s_addc_u32 s7, s7, 0
	s_waitcnt vmcnt(16)
	v_lshlrev_b32_e32 v202, 16, v114
	v_and_b32_e32 v203, s14, v114
	v_lshlrev_b32_e32 v204, 16, v122
	v_and_b32_e32 v205, s14, v122
	v_pk_mul_f32 v[52:53], v[202:203], v[204:205]
	v_lshlrev_b32_e32 v206, 16, v115
	v_and_b32_e32 v207, s14, v115
	v_lshlrev_b32_e32 v208, 16, v123
	v_and_b32_e32 v209, s14, v123
	v_pk_mul_f32 v[54:55], v[206:207], v[208:209]
	v_lshlrev_b32_e32 v210, 16, v116
	v_and_b32_e32 v211, s14, v116
	v_lshlrev_b32_e32 v212, 16, v124
	v_and_b32_e32 v213, s14, v124
	v_pk_mul_f32 v[56:57], v[210:211], v[212:213]
	v_lshlrev_b32_e32 v202, 16, v117
	v_and_b32_e32 v203, s14, v117
	v_lshlrev_b32_e32 v204, 16, v125
	v_and_b32_e32 v205, s14, v125
	v_pk_mul_f32 v[58:59], v[202:203], v[204:205]
	v_lshlrev_b32_e32 v206, 16, v118
	v_and_b32_e32 v207, s14, v118
	v_lshlrev_b32_e32 v208, 16, v126
	v_and_b32_e32 v209, s14, v126
	v_pk_mul_f32 v[60:61], v[206:207], v[208:209]
	v_lshlrev_b32_e32 v210, 16, v119
	v_and_b32_e32 v211, s14, v119
	v_lshlrev_b32_e32 v212, 16, v127
	v_and_b32_e32 v213, s14, v127
	v_pk_mul_f32 v[62:63], v[210:211], v[212:213]
	v_lshlrev_b32_e32 v202, 16, v120
	v_and_b32_e32 v203, s14, v120
	v_lshlrev_b32_e32 v204, 16, v128
	v_and_b32_e32 v205, s14, v128
	v_pk_mul_f32 v[64:65], v[202:203], v[204:205]
	v_lshlrev_b32_e32 v206, 16, v121
	v_and_b32_e32 v207, s14, v121
	v_lshlrev_b32_e32 v208, 16, v129
	v_and_b32_e32 v209, s14, v129
	v_pk_mul_f32 v[66:67], v[206:207], v[208:209]
	global_load_dwordx4 v[114:117], v1, s[4:5] offset:2048 nt
	global_load_dwordx4 v[118:121], v1, s[4:5] offset:2064 nt
	global_load_dwordx4 v[122:125], v2, s[4:5] nt
	global_load_dwordx4 v[126:129], v2, s[4:5] offset:16 nt
	s_add_u32 s4, s4, 0x1800
	s_addc_u32 s5, s5, 0
	s_add_i32 s12, s11, 4
	s_cmp_lt_u32 s12, 0x4000
	s_cselect_b32 s29, s3, s13
	s_and_b32 s27, s12, s29
	v_pk_mul_f32 v[234:235], v[20:21], v[98:99]
	v_pk_mul_f32 v[236:237], v[22:23], v[100:101]
	v_pk_mul_f32 v[238:239], v[24:25], v[102:103]
	v_pk_mul_f32 v[240:241], v[26:27], v[104:105]
	v_pk_mul_f32 v[242:243], v[28:29], v[106:107]
	v_pk_mul_f32 v[244:245], v[30:31], v[108:109]
	v_pk_mul_f32 v[246:247], v[32:33], v[110:111]
	v_pk_mul_f32 v[248:249], v[34:35], v[112:113]
	s_cmp_eq_u32 s27, 0
	s_cbranch_scc1 .Lcg9_np4
	v_pk_fma_f32 v[234:235], v[4:5], v[68:69], v[234:235]
	v_pk_fma_f32 v[236:237], v[6:7], v[70:71], v[236:237]
	v_pk_fma_f32 v[238:239], v[8:9], v[72:73], v[238:239]
	v_pk_fma_f32 v[240:241], v[10:11], v[74:75], v[240:241]
	v_pk_fma_f32 v[242:243], v[12:13], v[76:77], v[242:243]
	v_pk_fma_f32 v[244:245], v[14:15], v[78:79], v[244:245]
	v_pk_fma_f32 v[246:247], v[16:17], v[80:81], v[246:247]
	v_pk_fma_f32 v[248:249], v[18:19], v[82:83], v[248:249]

; __device__ __forceinline__ unsigned cvt_pk_bf16(float lo, float hi) { unsigned r; asm volatile("v_cvt_pk_bf16_f32 %0, %1, %2" : "=v"(r) : "v"(lo), "v"(hi)); return r; }
; __device__ __forceinline__ float bflo(unsigned w) { return __uint_as_float(w << 16); }
; __device__ __forceinline__ float bfhi(unsigned w) { return __uint_as_float(w & 0xffff0000u); }
; __device__ __forceinline__ void convgate_phase(const bf16_t* U, bf16_t* H, int rows, const float* ck, int gw, int NGW, int lane) {
;     for (int row = gw; row < rows; row += NGW) {
;         const bool lat = row < ML; const int t = lat ? (row & (SEQ - 1)) : ((row - ML) & (CL - 1)); const int L = lat ? SEQ : CL;
;         const bool hasp = t > 0, hasn = t < L - 1;
;         const bf16_t* ur = U + (size_t)row * 3072;
;         u32x4 bq[2], cq[2], vq[2], cp[2], vp[2], cn[2], vn[2];
; #pragma unroll
;         for (int hf = 0; hf < 2; ++hf) {
;             const int c0 = lane * 16 + hf * 8;
;             bq[hf] = *(const u32x4*)(ur + c0); cq[hf] = *(const u32x4*)(ur + 1024 + c0); vq[hf] = *(const u32x4*)(ur + 2048 + c0);
;             cp[hf] = (u32x4){0, 0, 0, 0}; vp[hf] = cp[hf]; cn[hf] = cp[hf]; vn[hf] = cp[hf];
;             if (hasp) { cp[hf] = *(const u32x4*)(ur - 3072 + 1024 + c0); vp[hf] = *(const u32x4*)(ur - 3072 + 2048 + c0); }
;             if (hasn) { cn[hf] = *(const u32x4*)(ur + 3072 + 1024 + c0); vn[hf] = *(const u32x4*)(ur + 3072 + 2048 + c0); }
;         }
; #pragma unroll
;         for (int hf = 0; hf < 2; ++hf) {
;             const int c0 = lane * 16 + hf * 8;
;             u32x4 ow;
; #pragma unroll
;             for (int e = 0; e < 4; ++e) {
;                 const f32x2 w0 = *(const f32x2*)(ck + c0 + 2 * e), w1 = *(const f32x2*)(ck + D + c0 + 2 * e), w2 = *(const f32x2*)(ck + 2 * D + c0 + 2 * e);
;                 const float lo = bflo(bq[hf][e]) * (w0[0] * (bflo(cp[hf][e]) * bflo(vp[hf][e])) + w1[0] * (bflo(cq[hf][e]) * bflo(vq[hf][e])) + w2[0] * (bflo(cn[hf][e]) * bflo(vn[hf][e])));
;                 const float hi = bfhi(bq[hf][e]) * (w0[1] * (bfhi(cp[hf][e]) * bfhi(vp[hf][e])) + w1[1] * (bfhi(cq[hf][e]) * bfhi(vq[hf][e])) + w2[1] * (bfhi(cn[hf][e]) * bfhi(vn[hf][e])));
;                 ow[e] = cvt_pk_bf16(lo, hi);
;             }
;             *(u32x4*)(H + (size_t)row * D + c0) = ow;
;         }
.Lcg9_nn4:
	v_lshlrev_b32_e32 v202, 16, v176
	v_and_b32_e32 v203, s14, v176
	v_pk_mul_f32 v[234:235], v[234:235], v[202:203]
	v_lshlrev_b32_e32 v206, 16, v177
	v_and_b32_e32 v207, s14, v177
	v_pk_mul_f32 v[236:237], v[236:237], v[206:207]
	v_lshlrev_b32_e32 v210, 16, v178
	v_and_b32_e32 v211, s14, v178
	v_pk_mul_f32 v[238:239], v[238:239], v[210:211]
	v_lshlrev_b32_e32 v202, 16, v179
	v_and_b32_e32 v203, s14, v179
	v_pk_mul_f32 v[240:241], v[240:241], v[202:203]
	v_lshlrev_b32_e32 v206, 16, v180
	v_and_b32_e32 v207, s14, v180
	v_pk_mul_f32 v[242:243], v[242:243], v[206:207]
	v_lshlrev_b32_e32 v210, 16, v181
	v_and_b32_e32 v211, s14, v181
	v_pk_mul_f32 v[244:245], v[244:245], v[210:211]
	v_lshlrev_b32_e32 v202, 16, v182
	v_and_b32_e32 v203, s14, v182
	v_pk_mul_f32 v[246:247], v[246:247], v[202:203]
	v_lshlrev_b32_e32 v206, 16, v183
	v_and_b32_e32 v207, s14, v183
	v_pk_mul_f32 v[248:249], v[248:249], v[206:207]
	v_cvt_pk_bf16_f32 v84, v234, v235
	v_cvt_pk_bf16_f32 v85, v236, v237
	v_cvt_pk_bf16_f32 v86, v238, v239
	v_cvt_pk_bf16_f32 v87, v240, v241
	v_cvt_pk_bf16_f32 v88, v242, v243
	v_cvt_pk_bf16_f32 v89, v244, v245
	v_cvt_pk_bf16_f32 v90, v246, v247
	v_cvt_pk_bf16_f32 v91, v248, v249
	global_store_dwordx4 v1, v[84:87], s[8:9]
	global_store_dwordx4 v1, v[88:91], s[8:9] offset:16
	s_add_u32 s8, s8, 0x800
	s_addc_u32 s9, s9, 0
	global_load_dwordx4 v[176:179], v1, s[6:7] nt
	global_load_dwordx4 v[180:183], v1, s[6:7] offset:16 nt
	s_add_u32 s6, s6, 0x1800
	s_addc_u32 s7, s7, 0
	s_waitcnt vmcnt(16)
	v_lshlrev_b32_e32 v202, 16, v130
	v_and_b32_e32 v203, s14, v130
	v_lshlrev_b32_e32 v204, 16, v138
	v_and_b32_e32 v205, s14, v138
	v_pk_mul_f32 v[68:69], v[202:203], v[204:205]
	v_lshlrev_b32_e32 v206, 16, v131
	v_and_b32_e32 v207, s14, v131
	v_lshlrev_b32_e32 v208, 16, v139
	v_and_b32_e32 v209, s14, v139
	v_pk_mul_f32 v[70:71], v[206:207], v[208:209]
	v_lshlrev_b32_e32 v210, 16, v132
	v_and_b32_e32 v211, s14, v132
	v_lshlrev_b32_e32 v212, 16, v140
	v_and_b32_e32 v213, s14, v140
	v_pk_mul_f32 v[72:73], v[210:211], v[212:213]
	v_lshlrev_b32_e32 v202, 16, v133
	v_and_b32_e32 v203, s14, v133
	v_lshlrev_b32_e32 v204, 16, v141
	v_and_b32_e32 v205, s14, v141
	v_pk_mul_f32 v[74:75], v[202:203], v[204:205]
	v_lshlrev_b32_e32 v206, 16, v134
	v_and_b32_e32 v207, s14, v134
	v_lshlrev_b32_e32 v208, 16, v142
	v_and_b32_e32 v209, s14, v142
	v_pk_mul_f32 v[76:77], v[206:207], v[208:209]
	v_lshlrev_b32_e32 v210, 16, v135
	v_and_b32_e32 v211, s14, v135
	v_lshlrev_b32_e32 v212, 16, v143
	v_and_b32_e32 v213, s14, v143
	v_pk_mul_f32 v[78:79], v[210:211], v[212:213]
	v_lshlrev_b32_e32 v202, 16, v136
	v_and_b32_e32 v203, s14, v136
	v_lshlrev_b32_e32 v204, 16, v144
	v_and_b32_e32 v205, s14, v144
	v_pk_mul_f32 v[80:81], v[202:203], v[204:205]
	v_lshlrev_b32_e32 v206, 16, v137
	v_and_b32_e32 v207, s14, v137
	v_lshlrev_b32_e32 v208, 16, v145
	v_and_b32_e32 v209, s14, v145
	v_pk_mul_f32 v[82:83], v[206:207], v[208:209]
	global_load_dwordx4 v[130:133], v1, s[4:5] offset:2048 nt
	global_load_dwordx4 v[134:137], v1, s[4:5] offset:2064 nt
	global_load_dwordx4 v[138:141], v2, s[4:5] nt
	global_load_dwordx4 v[142:145], v2, s[4:5] offset:16 nt
	s_add_u32 s4, s4, 0x1800
	s_addc_u32 s5, s5, 0
	s_add_i32 s12, s11, 5
	s_cmp_lt_u32 s12, 0x4000
	s_cselect_b32 s29, s3, s13
	s_and_b32 s27, s12, s29
	v_pk_mul_f32 v[234:235], v[20:21], v[52:53]
	v_pk_mul_f32 v[236:237], v[22:23], v[54:55]
	v_pk_mul_f32 v[238:239], v[24:25], v[56:57]
	v_pk_mul_f32 v[240:241], v[26:27], v[58:59]
	v_pk_mul_f32 v[242:243], v[28:29], v[60:61]
	v_pk_mul_f32 v[244:245], v[30:31], v[62:63]
	v_pk_mul_f32 v[246:247], v[32:33], v[64:65]
	v_pk_mul_f32 v[248:249], v[34:35], v[66:67]
	s_cmp_eq_u32 s27, 0
	s_cbranch_scc1 .Lcg9_np5
	v_pk_fma_f32 v[234:235], v[4:5], v[98:99], v[234:235]
	v_pk_fma_f32 v[236:237], v[6:7], v[100:101], v[236:237]
	v_pk_fma_f32 v[238:239], v[8:9], v[102:103], v[238:239]
	v_pk_fma_f32 v[240:241], v[10:11], v[104:105], v[240:241]
	v_pk_fma_f32 v[242:243], v[12:13], v[106:107], v[242:243]
	v_pk_fma_f32 v[244:245], v[14:15], v[108:109], v[244:245]
	v_pk_fma_f32 v[246:247], v[16:17], v[110:111], v[246:247]
	v_pk_fma_f32 v[248:249], v[18:19], v[112:113], v[248:249]

; __device__ __forceinline__ unsigned cvt_pk_bf16(float lo, float hi) { unsigned r; asm volatile("v_cvt_pk_bf16_f32 %0, %1, %2" : "=v"(r) : "v"(lo), "v"(hi)); return r; }
; __device__ __forceinline__ float bflo(unsigned w) { return __uint_as_float(w << 16); }
; __device__ __forceinline__ float bfhi(unsigned w) { return __uint_as_float(w & 0xffff0000u); }
; __device__ __forceinline__ void convgate_phase(const bf16_t* U, bf16_t* H, int rows, const float* ck, int gw, int NGW, int lane) {
;     for (int row = gw; row < rows; row += NGW) {
;         const bool lat = row < ML; const int t = lat ? (row & (SEQ - 1)) : ((row - ML) & (CL - 1)); const int L = lat ? SEQ : CL;
;         const bool hasp = t > 0, hasn = t < L - 1;
;         const bf16_t* ur = U + (size_t)row * 3072;
;         u32x4 bq[2], cq[2], vq[2], cp[2], vp[2], cn[2], vn[2];
; #pragma unroll
;         for (int hf = 0; hf < 2; ++hf) {
;             const int c0 = lane * 16 + hf * 8;
;             bq[hf] = *(const u32x4*)(ur + c0); cq[hf] = *(const u32x4*)(ur + 1024 + c0); vq[hf] = *(const u32x4*)(ur + 2048 + c0);
;             cp[hf] = (u32x4){0, 0, 0, 0}; vp[hf] = cp[hf]; cn[hf] = cp[hf]; vn[hf] = cp[hf];
;             if (hasp) { cp[hf] = *(const u32x4*)(ur - 3072 + 1024 + c0); vp[hf] = *(const u32x4*)(ur - 3072 + 2048 + c0); }
;             if (hasn) { cn[hf] = *(const u32x4*)(ur + 3072 + 1024 + c0); vn[hf] = *(const u32x4*)(ur + 3072 + 2048 + c0); }
;         }
; #pragma unroll
;         for (int hf = 0; hf < 2; ++hf) {
;             const int c0 = lane * 16 + hf * 8;
;             u32x4 ow;
; #pragma unroll
;             for (int e = 0; e < 4; ++e) {
;                 const f32x2 w0 = *(const f32x2*)(ck + c0 + 2 * e), w1 = *(const f32x2*)(ck + D + c0 + 2 * e), w2 = *(const f32x2*)(ck + 2 * D + c0 + 2 * e);
;                 const float lo = bflo(bq[hf][e]) * (w0[0] * (bflo(cp[hf][e]) * bflo(vp[hf][e])) + w1[0] * (bflo(cq[hf][e]) * bflo(vq[hf][e])) + w2[0] * (bflo(cn[hf][e]) * bflo(vn[hf][e])));
;                 const float hi = bfhi(bq[hf][e]) * (w0[1] * (bfhi(cp[hf][e]) * bfhi(vp[hf][e])) + w1[1] * (bfhi(cq[hf][e]) * bfhi(vq[hf][e])) + w2[1] * (bfhi(cn[hf][e]) * bfhi(vn[hf][e])));
;                 ow[e] = cvt_pk_bf16(lo, hi);
;             }
;             *(u32x4*)(H + (size_t)row * D + c0) = ow;
;         }
.Lcg9_nn5:
	v_lshlrev_b32_e32 v202, 16, v226
	v_and_b32_e32 v203, s14, v226
	v_pk_mul_f32 v[234:235], v[234:235], v[202:203]
	v_lshlrev_b32_e32 v206, 16, v227
	v_and_b32_e32 v207, s14, v227
	v_pk_mul_f32 v[236:237], v[236:237], v[206:207]
	v_lshlrev_b32_e32 v210, 16, v228
	v_and_b32_e32 v211, s14, v228
	v_pk_mul_f32 v[238:239], v[238:239], v[210:211]
	v_lshlrev_b32_e32 v202, 16, v229
	v_and_b32_e32 v203, s14, v229
	v_pk_mul_f32 v[240:241], v[240:241], v[202:203]
	v_lshlrev_b32_e32 v206, 16, v230
	v_and_b32_e32 v207, s14, v230
	v_pk_mul_f32 v[242:243], v[242:243], v[206:207]
	v_lshlrev_b32_e32 v210, 16, v231
	v_and_b32_e32 v211, s14, v231
	v_pk_mul_f32 v[244:245], v[244:245], v[210:211]
	v_lshlrev_b32_e32 v202, 16, v232
	v_and_b32_e32 v203, s14, v232
	v_pk_mul_f32 v[246:247], v[246:247], v[202:203]
	v_lshlrev_b32_e32 v206, 16, v233
	v_and_b32_e32 v207, s14, v233
	v_pk_mul_f32 v[248:249], v[248:249], v[206:207]
	v_cvt_pk_bf16_f32 v84, v234, v235
	v_cvt_pk_bf16_f32 v85, v236, v237
	v_cvt_pk_bf16_f32 v86, v238, v239
	v_cvt_pk_bf16_f32 v87, v240, v241
	v_cvt_pk_bf16_f32 v88, v242, v243
	v_cvt_pk_bf16_f32 v89, v244, v245
	v_cvt_pk_bf16_f32 v90, v246, v247
	v_cvt_pk_bf16_f32 v91, v248, v249
	global_store_dwordx4 v1, v[84:87], s[8:9]
	global_store_dwordx4 v1, v[88:91], s[8:9] offset:16
	s_add_u32 s8, s8, 0x800
	s_addc_u32 s9, s9, 0
	global_load_dwordx4 v[226:229], v1, s[6:7] nt
	global_load_dwordx4 v[230:233], v1, s[6:7] offset:16 nt
	s_add_u32 s6, s6, 0x1800
	s_addc_u32 s7, s7, 0
	s_waitcnt vmcnt(16)
	v_lshlrev_b32_e32 v202, 16, v160
	v_and_b32_e32 v203, s14, v160
	v_lshlrev_b32_e32 v204, 16, v168
	v_and_b32_e32 v205, s14, v168
	v_pk_mul_f32 v[98:99], v[202:203], v[204:205]
	v_lshlrev_b32_e32 v206, 16, v161
	v_and_b32_e32 v207, s14, v161
	v_lshlrev_b32_e32 v208, 16, v169
	v_and_b32_e32 v209, s14, v169
	v_pk_mul_f32 v[100:101], v[206:207], v[208:209]
	v_lshlrev_b32_e32 v210, 16, v162
	v_and_b32_e32 v211, s14, v162
	v_lshlrev_b32_e32 v212, 16, v170
	v_and_b32_e32 v213, s14, v170
	v_pk_mul_f32 v[102:103], v[210:211], v[212:213]
	v_lshlrev_b32_e32 v202, 16, v163
	v_and_b32_e32 v203, s14, v163
	v_lshlrev_b32_e32 v204, 16, v171
	v_and_b32_e32 v205, s14, v171
	v_pk_mul_f32 v[104:105], v[202:203], v[204:205]
	v_lshlrev_b32_e32 v206, 16, v164
	v_and_b32_e32 v207, s14, v164
	v_lshlrev_b32_e32 v208, 16, v172
	v_and_b32_e32 v209, s14, v172
	v_pk_mul_f32 v[106:107], v[206:207], v[208:209]
	v_lshlrev_b32_e32 v210, 16, v165
	v_and_b32_e32 v211, s14, v165
	v_lshlrev_b32_e32 v212, 16, v173
	v_and_b32_e32 v213, s14, v173
	v_pk_mul_f32 v[108:109], v[210:211], v[212:213]
	v_lshlrev_b32_e32 v202, 16, v166
	v_and_b32_e32 v203, s14, v166
	v_lshlrev_b32_e32 v204, 16, v174
	v_and_b32_e32 v205, s14, v174
	v_pk_mul_f32 v[110:111], v[202:203], v[204:205]
	v_lshlrev_b32_e32 v206, 16, v167
	v_and_b32_e32 v207, s14, v167
	v_lshlrev_b32_e32 v208, 16, v175
	v_and_b32_e32 v209, s14, v175
	v_pk_mul_f32 v[112:113], v[206:207], v[208:209]
	s_add_i32 s12, s11, 6
	s_cmp_lt_u32 s12, 0x4000
	s_cselect_b32 s29, s3, s13
	s_and_b32 s27, s12, s29
	v_pk_mul_f32 v[234:235], v[20:21], v[68:69]
	v_pk_mul_f32 v[236:237], v[22:23], v[70:71]
	v_pk_mul_f32 v[238:239], v[24:25], v[72:73]
	v_pk_mul_f32 v[240:241], v[26:27], v[74:75]
	v_pk_mul_f32 v[242:243], v[28:29], v[76:77]
	v_pk_mul_f32 v[244:245], v[30:31], v[78:79]
	v_pk_mul_f32 v[246:247], v[32:33], v[80:81]
	v_pk_mul_f32 v[248:249], v[34:35], v[82:83]
	s_cmp_eq_u32 s27, 0
	s_cbranch_scc1 .Lcg9_np6
	v_pk_fma_f32 v[234:235], v[4:5], v[52:53], v[234:235]
	v_pk_fma_f32 v[236:237], v[6:7], v[54:55], v[236:237]
	v_pk_fma_f32 v[238:239], v[8:9], v[56:57], v[238:239]
	v_pk_fma_f32 v[240:241], v[10:11], v[58:59], v[240:241]
	v_pk_fma_f32 v[242:243], v[12:13], v[60:61], v[242:243]
	v_pk_fma_f32 v[244:245], v[14:15], v[62:63], v[244:245]
	v_pk_fma_f32 v[246:247], v[16:17], v[64:65], v[246:247]
	v_pk_fma_f32 v[248:249], v[18:19], v[66:67], v[248:249]

; __device__ __forceinline__ unsigned cvt_pk_bf16(float lo, float hi) { unsigned r; asm volatile("v_cvt_pk_bf16_f32 %0, %1, %2" : "=v"(r) : "v"(lo), "v"(hi)); return r; }
; __device__ __forceinline__ float bflo(unsigned w) { return __uint_as_float(w << 16); }
; __device__ __forceinline__ float bfhi(unsigned w) { return __uint_as_float(w & 0xffff0000u); }
; __device__ __forceinline__ void convgate_phase(const bf16_t* U, bf16_t* H, int rows, const float* ck, int gw, int NGW, int lane) {
;     for (int row = gw; row < rows; row += NGW) {
;         const bool lat = row < ML; const int t = lat ? (row & (SEQ - 1)) : ((row - ML) & (CL - 1)); const int L = lat ? SEQ : CL;
;         const bool hasp = t > 0, hasn = t < L - 1;
;         const bf16_t* ur = U + (size_t)row * 3072;
;         u32x4 bq[2], cq[2], vq[2], cp[2], vp[2], cn[2], vn[2];
; #pragma unroll
;         for (int hf = 0; hf < 2; ++hf) {
;             const int c0 = lane * 16 + hf * 8;
;             bq[hf] = *(const u32x4*)(ur + c0); cq[hf] = *(const u32x4*)(ur + 1024 + c0); vq[hf] = *(const u32x4*)(ur + 2048 + c0);
;             cp[hf] = (u32x4){0, 0, 0, 0}; vp[hf] = cp[hf]; cn[hf] = cp[hf]; vn[hf] = cp[hf];
;             if (hasp) { cp[hf] = *(const u32x4*)(ur - 3072 + 1024 + c0); vp[hf] = *(const u32x4*)(ur - 3072 + 2048 + c0); }
;             if (hasn) { cn[hf] = *(const u32x4*)(ur + 3072 + 1024 + c0); vn[hf] = *(const u32x4*)(ur + 3072 + 2048 + c0); }
;         }
; #pragma unroll
;         for (int hf = 0; hf < 2; ++hf) {
;             const int c0 = lane * 16 + hf * 8;
;             u32x4 ow;
; #pragma unroll
;             for (int e = 0; e < 4; ++e) {
;                 const f32x2 w0 = *(const f32x2*)(ck + c0 + 2 * e), w1 = *(const f32x2*)(ck + D + c0 + 2 * e), w2 = *(const f32x2*)(ck + 2 * D + c0 + 2 * e);
;                 const float lo = bflo(bq[hf][e]) * (w0[0] * (bflo(cp[hf][e]) * bflo(vp[hf][e])) + w1[0] * (bflo(cq[hf][e]) * bflo(vq[hf][e])) + w2[0] * (bflo(cn[hf][e]) * bflo(vn[hf][e])));
;                 const float hi = bfhi(bq[hf][e]) * (w0[1] * (bfhi(cp[hf][e]) * bfhi(vp[hf][e])) + w1[1] * (bfhi(cq[hf][e]) * bfhi(vq[hf][e])) + w2[1] * (bfhi(cn[hf][e]) * bfhi(vn[hf][e])));
;                 ow[e] = cvt_pk_bf16(lo, hi);
;             }
;             *(u32x4*)(H + (size_t)row * D + c0) = ow;
;         }
.Lcg8_nn4:
	v_lshlrev_b32_e32 v202, 16, v176
	v_and_b32_e32 v203, s14, v176
	v_pk_mul_f32 v[234:235], v[234:235], v[202:203]
	v_lshlrev_b32_e32 v206, 16, v177
	v_and_b32_e32 v207, s14, v177
	v_pk_mul_f32 v[236:237], v[236:237], v[206:207]
	v_lshlrev_b32_e32 v210, 16, v178
	v_and_b32_e32 v211, s14, v178
	v_pk_mul_f32 v[238:239], v[238:239], v[210:211]
	v_lshlrev_b32_e32 v202, 16, v179
	v_and_b32_e32 v203, s14, v179
	v_pk_mul_f32 v[240:241], v[240:241], v[202:203]
	v_lshlrev_b32_e32 v206, 16, v180
	v_and_b32_e32 v207, s14, v180
	v_pk_mul_f32 v[242:243], v[242:243], v[206:207]
	v_lshlrev_b32_e32 v210, 16, v181
	v_and_b32_e32 v211, s14, v181
	v_pk_mul_f32 v[244:245], v[244:245], v[210:211]
	v_lshlrev_b32_e32 v202, 16, v182
	v_and_b32_e32 v203, s14, v182
	v_pk_mul_f32 v[246:247], v[246:247], v[202:203]
	v_lshlrev_b32_e32 v206, 16, v183
	v_and_b32_e32 v207, s14, v183
	v_pk_mul_f32 v[248:249], v[248:249], v[206:207]
	v_cvt_pk_bf16_f32 v84, v234, v235
	v_cvt_pk_bf16_f32 v85, v236, v237
	v_cvt_pk_bf16_f32 v86, v238, v239
	v_cvt_pk_bf16_f32 v87, v240, v241
	v_cvt_pk_bf16_f32 v88, v242, v243
	v_cvt_pk_bf16_f32 v89, v244, v245
	v_cvt_pk_bf16_f32 v90, v246, v247
	v_cvt_pk_bf16_f32 v91, v248, v249
	global_store_dwordx4 v1, v[84:87], s[8:9]
	global_store_dwordx4 v1, v[88:91], s[8:9] offset:16
	s_add_u32 s8, s8, 0x800
	s_addc_u32 s9, s9, 0
	global_load_dwordx4 v[176:179], v1, s[6:7] nt
	global_load_dwordx4 v[180:183], v1, s[6:7] offset:16 nt
	s_add_u32 s6, s6, 0x1800
	s_addc_u32 s7, s7, 0
	s_waitcnt vmcnt(16)
	v_lshlrev_b32_e32 v202, 16, v130
	v_and_b32_e32 v203, s14, v130
	v_lshlrev_b32_e32 v204, 16, v138
	v_and_b32_e32 v205, s14, v138
	v_pk_mul_f32 v[68:69], v[202:203], v[204:205]
	v_lshlrev_b32_e32 v206, 16, v131
	v_and_b32_e32 v207, s14, v131
	v_lshlrev_b32_e32 v208, 16, v139
	v_and_b32_e32 v209, s14, v139
	v_pk_mul_f32 v[70:71], v[206:207], v[208:209]
	v_lshlrev_b32_e32 v210, 16, v132
	v_and_b32_e32 v211, s14, v132
	v_lshlrev_b32_e32 v212, 16, v140
	v_and_b32_e32 v213, s14, v140
	v_pk_mul_f32 v[72:73], v[210:211], v[212:213]
	v_lshlrev_b32_e32 v202, 16, v133
	v_and_b32_e32 v203, s14, v133
	v_lshlrev_b32_e32 v204, 16, v141
	v_and_b32_e32 v205, s14, v141
	v_pk_mul_f32 v[74:75], v[202:203], v[204:205]
	v_lshlrev_b32_e32 v206, 16, v134
	v_and_b32_e32 v207, s14, v134
	v_lshlrev_b32_e32 v208, 16, v142
	v_and_b32_e32 v209, s14, v142
	v_pk_mul_f32 v[76:77], v[206:207], v[208:209]
	v_lshlrev_b32_e32 v210, 16, v135
	v_and_b32_e32 v211, s14, v135
	v_lshlrev_b32_e32 v212, 16, v143
	v_and_b32_e32 v213, s14, v143
	v_pk_mul_f32 v[78:79], v[210:211], v[212:213]
	v_lshlrev_b32_e32 v202, 16, v136
	v_and_b32_e32 v203, s14, v136
	v_lshlrev_b32_e32 v204, 16, v144
	v_and_b32_e32 v205, s14, v144
	v_pk_mul_f32 v[80:81], v[202:203], v[204:205]
	v_lshlrev_b32_e32 v206, 16, v137
	v_and_b32_e32 v207, s14, v137
	v_lshlrev_b32_e32 v208, 16, v145
	v_and_b32_e32 v209, s14, v145
	v_pk_mul_f32 v[82:83], v[206:207], v[208:209]
	s_add_i32 s12, s11, 5
	s_cmp_lt_u32 s12, 0x4000
	s_cselect_b32 s29, s3, s13
	s_and_b32 s27, s12, s29
	v_pk_mul_f32 v[234:235], v[20:21], v[52:53]
	v_pk_mul_f32 v[236:237], v[22:23], v[54:55]
	v_pk_mul_f32 v[238:239], v[24:25], v[56:57]
	v_pk_mul_f32 v[240:241], v[26:27], v[58:59]
	v_pk_mul_f32 v[242:243], v[28:29], v[60:61]
	v_pk_mul_f32 v[244:245], v[30:31], v[62:63]
	v_pk_mul_f32 v[246:247], v[32:33], v[64:65]
	v_pk_mul_f32 v[248:249], v[34:35], v[66:67]
	s_cmp_eq_u32 s27, 0
	s_cbranch_scc1 .Lcg8_np5
	v_pk_fma_f32 v[234:235], v[4:5], v[98:99], v[234:235]
	v_pk_fma_f32 v[236:237], v[6:7], v[100:101], v[236:237]
	v_pk_fma_f32 v[238:239], v[8:9], v[102:103], v[238:239]
	v_pk_fma_f32 v[240:241], v[10:11], v[104:105], v[240:241]
	v_pk_fma_f32 v[242:243], v[12:13], v[106:107], v[242:243]
	v_pk_fma_f32 v[244:245], v[14:15], v[108:109], v[244:245]
	v_pk_fma_f32 v[246:247], v[16:17], v[110:111], v[246:247]
	v_pk_fma_f32 v[248:249], v[18:19], v[112:113], v[248:249]

; __device__ __forceinline__ unsigned cvt_pk_bf16(float lo, float hi) { unsigned r; asm volatile("v_cvt_pk_bf16_f32 %0, %1, %2" : "=v"(r) : "v"(lo), "v"(hi)); return r; }
;     __device__ __forceinline__ void operator()(const f32x4 (&acc)[2][2][4][2], const Unit& u, int wr, int wc, int fr, int fq) const {
;     ...
;         const unsigned ldb = (unsigned)ldc * 2u; const float sc_ = (u.pn < scale_tiles) ? scale : 1.0f;
;         unsigned off0 = (unsigned)(wr * 64 + fr) * ldb + (unsigned)(wc * 32 + 8 * fq) * 2u; asm volatile("" : "+v"(off0));
; #pragma unroll
;         for (int ai = 0; ai < 2; ++ai)
; #pragma unroll
;             for (int m = 0; m < 4; ++m) { const unsigned off = off0 + (unsigned)(ai * HALF + m * 16) * ldb;
; #pragma unroll
;                 for (int bj = 0; bj < 2; ++bj) { const f32x4 v0 = acc[ai][bj][m][0] * sc_, v1 = acc[ai][bj][m][1] * sc_;
;                     u32x4 w; w.x = cvt_pk_bf16(v0[0], v0[1]); w.y = cvt_pk_bf16(v0[2], v0[3]); w.z = cvt_pk_bf16(v1[0], v1[1]); w.w = cvt_pk_bf16(v1[2], v1[3]);
;                     *(u32x4*)(base + off + bj * HALF * 2) = w;
.LBB0_1085:
	s_lshl_b32 s22, s58, 8
	s_mul_hi_i32 s23, s22, s47
	s_mul_i32 s22, s22, s47
	s_lshl_b64 s[22:23], s[22:23], 1
	s_add_u32 s24, s8, s22
	s_addc_u32 s25, s9, s23
	s_lshl_b32 s22, s54, 8
	s_ashr_i32 s23, s22, 31
	s_lshl_b64 s[22:23], s[22:23], 1
	s_add_u32 s22, s24, s22
	s_addc_u32 s23, s25, s23
	s_cmp_lt_i32 s54, s48
	s_cselect_b64 vcc, -1, 0
	v_cndmask_b32_e32 v140, 1.0, v144, vcc
	v_mov_b32_e32 v150, v146
	v_pk_mul_f32 v[128:129], v[140:141], v[128:129] op_sel_hi:[0,1]
	v_pk_mul_f32 v[126:127], v[140:141], v[126:127] op_sel_hi:[0,1]
	v_pk_mul_f32 v[148:149], v[140:141], v[124:125] op_sel_hi:[0,1]
	v_pk_mul_f32 v[124:125], v[140:141], v[122:123] op_sel_hi:[0,1]
	v_cvt_pk_bf16_f32 v122, v126, v127
	v_cvt_pk_bf16_f32 v123, v128, v129
	v_cvt_pk_bf16_f32 v124, v124, v125
	v_cvt_pk_bf16_f32 v125, v148, v149
	global_store_dwordx4 v150, v[122:125], s[22:23] nt
	v_pk_mul_f32 v[120:121], v[140:141], v[120:121] op_sel_hi:[0,1]
	v_pk_mul_f32 v[118:119], v[140:141], v[118:119] op_sel_hi:[0,1]
	v_pk_mul_f32 v[122:123], v[140:141], v[112:113] op_sel_hi:[0,1]
	v_pk_mul_f32 v[112:113], v[140:141], v[110:111] op_sel_hi:[0,1]
	v_cvt_pk_bf16_f32 v110, v118, v119
	v_cvt_pk_bf16_f32 v111, v120, v121
	v_cvt_pk_bf16_f32 v112, v112, v113
	v_cvt_pk_bf16_f32 v113, v122, v123
	global_store_dwordx4 v150, v[110:113], s[22:23] offset:256 nt
	v_add_u32_e32 v118, s82, v150
	v_pk_mul_f32 v[104:105], v[140:141], v[104:105] op_sel_hi:[0,1]
	v_pk_mul_f32 v[110:111], v[140:141], v[116:117] op_sel_hi:[0,1]
	v_pk_mul_f32 v[112:113], v[140:141], v[114:115] op_sel_hi:[0,1]
	v_pk_mul_f32 v[114:115], v[140:141], v[108:109] op_sel_hi:[0,1]
	v_pk_mul_f32 v[108:109], v[140:141], v[106:107] op_sel_hi:[0,1]
	v_cvt_pk_bf16_f32 v106, v112, v113
	v_cvt_pk_bf16_f32 v107, v110, v111
	v_cvt_pk_bf16_f32 v108, v108, v109
	v_cvt_pk_bf16_f32 v109, v114, v115
	global_store_dwordx4 v118, v[106:109], s[22:23] nt
	v_pk_mul_f32 v[102:103], v[140:141], v[102:103] op_sel_hi:[0,1]
	v_pk_mul_f32 v[86:87], v[140:141], v[86:87] op_sel_hi:[0,1]
	v_pk_mul_f32 v[106:107], v[140:141], v[94:95] op_sel_hi:[0,1]
	v_pk_mul_f32 v[94:95], v[140:141], v[92:93] op_sel_hi:[0,1]
	v_cvt_pk_bf16_f32 v92, v102, v103
	v_cvt_pk_bf16_f32 v93, v104, v105
	v_cvt_pk_bf16_f32 v94, v94, v95
	v_cvt_pk_bf16_f32 v95, v106, v107
	global_store_dwordx4 v118, v[92:95], s[22:23] offset:256 nt
	v_add_u32_e32 v102, s82, v118
	v_pk_mul_f32 v[84:85], v[140:141], v[84:85] op_sel_hi:[0,1]
	v_pk_mul_f32 v[92:93], v[140:141], v[100:101] op_sel_hi:[0,1]
	v_pk_mul_f32 v[94:95], v[140:141], v[98:99] op_sel_hi:[0,1]
	v_pk_mul_f32 v[98:99], v[140:141], v[90:91] op_sel_hi:[0,1]
	v_pk_mul_f32 v[90:91], v[140:141], v[88:89] op_sel_hi:[0,1]
	v_cvt_pk_bf16_f32 v88, v94, v95
	v_cvt_pk_bf16_f32 v89, v92, v93
	v_cvt_pk_bf16_f32 v90, v90, v91
	v_cvt_pk_bf16_f32 v91, v98, v99
	global_store_dwordx4 v102, v[88:91], s[22:23] nt
	v_pk_mul_f32 v[70:71], v[140:141], v[70:71] op_sel_hi:[0,1]
	v_pk_mul_f32 v[68:69], v[140:141], v[68:69] op_sel_hi:[0,1]
	v_pk_mul_f32 v[88:89], v[140:141], v[78:79] op_sel_hi:[0,1]
	v_pk_mul_f32 v[78:79], v[140:141], v[76:77] op_sel_hi:[0,1]
	v_cvt_pk_bf16_f32 v76, v84, v85
	v_cvt_pk_bf16_f32 v77, v86, v87
	v_cvt_pk_bf16_f32 v78, v78, v79
	v_cvt_pk_bf16_f32 v79, v88, v89
	global_store_dwordx4 v102, v[76:79], s[22:23] offset:256 nt
	v_add_u32_e32 v84, s82, v102
	s_mul_i32 s24, s47, 0xa0
	v_pk_mul_f32 v[76:77], v[140:141], v[82:83] op_sel_hi:[0,1]
	v_pk_mul_f32 v[78:79], v[140:141], v[80:81] op_sel_hi:[0,1]
	v_pk_mul_f32 v[80:81], v[140:141], v[74:75] op_sel_hi:[0,1]
	v_pk_mul_f32 v[74:75], v[140:141], v[72:73] op_sel_hi:[0,1]
	v_cvt_pk_bf16_f32 v72, v78, v79
	v_cvt_pk_bf16_f32 v73, v76, v77
	v_cvt_pk_bf16_f32 v74, v74, v75
	v_cvt_pk_bf16_f32 v75, v80, v81
	global_store_dwordx4 v84, v[72:75], s[22:23] nt
	v_pk_mul_f32 v[62:63], v[140:141], v[62:63] op_sel_hi:[0,1]
	v_pk_mul_f32 v[60:61], v[140:141], v[60:61] op_sel_hi:[0,1]
; __device__ __forceinline__ unsigned cvt_pk_bf16(float lo, float hi) { unsigned r; asm volatile("v_cvt_pk_bf16_f32 %0, %1, %2" : "=v"(r) : "v"(lo), "v"(hi)); return r; }
;     __device__ __forceinline__ void operator()(const f32x4 (&acc)[2][2][4][2], const Unit& u, int wr, int wc, int fr, int fq) const {
;     ...
;         const unsigned ldb = (unsigned)ldc * 2u; const float sc_ = (u.pn < scale_tiles) ? scale : 1.0f;
;         unsigned off0 = (unsigned)(wr * 64 + fr) * ldb + (unsigned)(wc * 32 + 8 * fq) * 2u; asm volatile("" : "+v"(off0));
; #pragma unroll
;         for (int ai = 0; ai < 2; ++ai)
; #pragma unroll
;             for (int m = 0; m < 4; ++m) { const unsigned off = off0 + (unsigned)(ai * HALF + m * 16) * ldb;
; #pragma unroll
;                 for (int bj = 0; bj < 2; ++bj) { const f32x4 v0 = acc[ai][bj][m][0] * sc_, v1 = acc[ai][bj][m][1] * sc_;
;                     u32x4 w; w.x = cvt_pk_bf16(v0[0], v0[1]); w.y = cvt_pk_bf16(v0[2], v0[3]); w.z = cvt_pk_bf16(v1[0], v1[1]); w.w = cvt_pk_bf16(v1[2], v1[3]);
;                     *(u32x4*)(base + off + bj * HALF * 2) = w;
	v_pk_mul_f32 v[72:73], v[140:141], v[66:67] op_sel_hi:[0,1]
	v_pk_mul_f32 v[66:67], v[140:141], v[64:65] op_sel_hi:[0,1]
	v_cvt_pk_bf16_f32 v64, v68, v69
	v_cvt_pk_bf16_f32 v65, v70, v71
	v_cvt_pk_bf16_f32 v66, v66, v67
	v_cvt_pk_bf16_f32 v67, v72, v73
	global_store_dwordx4 v84, v[64:67], s[22:23] offset:256 nt
	v_pk_mul_f32 v[54:55], v[140:141], v[54:55] op_sel_hi:[0,1]
	v_pk_mul_f32 v[52:53], v[140:141], v[52:53] op_sel_hi:[0,1]
	v_add_u32_e32 v66, s24, v84
	v_pk_mul_f32 v[64:65], v[140:141], v[58:59] op_sel_hi:[0,1]
	v_pk_mul_f32 v[58:59], v[140:141], v[56:57] op_sel_hi:[0,1]
	v_cvt_pk_bf16_f32 v56, v60, v61
	v_cvt_pk_bf16_f32 v57, v62, v63
	v_cvt_pk_bf16_f32 v58, v58, v59
	v_cvt_pk_bf16_f32 v59, v64, v65
	global_store_dwordx4 v66, v[56:59], s[22:23] nt
	v_pk_mul_f32 v[38:39], v[140:141], v[38:39] op_sel_hi:[0,1]
	v_pk_mul_f32 v[36:37], v[140:141], v[36:37] op_sel_hi:[0,1]
	v_pk_mul_f32 v[56:57], v[140:141], v[46:47] op_sel_hi:[0,1]
	v_pk_mul_f32 v[46:47], v[140:141], v[44:45] op_sel_hi:[0,1]
	v_cvt_pk_bf16_f32 v44, v52, v53
	v_cvt_pk_bf16_f32 v45, v54, v55
	v_cvt_pk_bf16_f32 v46, v46, v47
	v_cvt_pk_bf16_f32 v47, v56, v57
	global_store_dwordx4 v66, v[44:47], s[22:23] offset:256 nt
	v_add_u32_e32 v52, s82, v66
	v_pk_mul_f32 v[22:23], v[140:141], v[22:23] op_sel_hi:[0,1]
	v_pk_mul_f32 v[44:45], v[140:141], v[50:51] op_sel_hi:[0,1]
	v_pk_mul_f32 v[46:47], v[140:141], v[48:49] op_sel_hi:[0,1]
	v_pk_mul_f32 v[48:49], v[140:141], v[42:43] op_sel_hi:[0,1]
	v_pk_mul_f32 v[42:43], v[140:141], v[40:41] op_sel_hi:[0,1]
	v_cvt_pk_bf16_f32 v40, v46, v47
	v_cvt_pk_bf16_f32 v41, v44, v45
	v_cvt_pk_bf16_f32 v42, v42, v43
	v_cvt_pk_bf16_f32 v43, v48, v49
	global_store_dwordx4 v52, v[40:43], s[22:23] nt
	v_pk_mul_f32 v[20:21], v[140:141], v[20:21] op_sel_hi:[0,1]
	s_andn2_b64 vcc, exec, s[4:5]
	v_pk_mul_f32 v[40:41], v[140:141], v[30:31] op_sel_hi:[0,1]
	v_pk_mul_f32 v[30:31], v[140:141], v[28:29] op_sel_hi:[0,1]
	v_cvt_pk_bf16_f32 v28, v36, v37
	v_cvt_pk_bf16_f32 v29, v38, v39
	v_cvt_pk_bf16_f32 v30, v30, v31
	v_cvt_pk_bf16_f32 v31, v40, v41
	global_store_dwordx4 v52, v[28:31], s[22:23] offset:256 nt
	v_add_u32_e32 v36, s82, v52
	s_mov_b64 s[4:5], -1
	v_pk_mul_f32 v[28:29], v[140:141], v[34:35] op_sel_hi:[0,1]
	v_pk_mul_f32 v[30:31], v[140:141], v[32:33] op_sel_hi:[0,1]
	v_pk_mul_f32 v[32:33], v[140:141], v[26:27] op_sel_hi:[0,1]
	v_pk_mul_f32 v[26:27], v[140:141], v[24:25] op_sel_hi:[0,1]
	v_cvt_pk_bf16_f32 v24, v30, v31
	v_cvt_pk_bf16_f32 v25, v28, v29
	v_cvt_pk_bf16_f32 v26, v26, v27
	v_cvt_pk_bf16_f32 v27, v32, v33
	global_store_dwordx4 v36, v[24:27], s[22:23] nt
	v_pk_mul_f32 v[6:7], v[140:141], v[6:7] op_sel_hi:[0,1]
	v_pk_mul_f32 v[4:5], v[140:141], v[4:5] op_sel_hi:[0,1]
	v_pk_mul_f32 v[24:25], v[140:141], v[14:15] op_sel_hi:[0,1]
	v_pk_mul_f32 v[14:15], v[140:141], v[12:13] op_sel_hi:[0,1]
	v_cvt_pk_bf16_f32 v12, v20, v21
	v_cvt_pk_bf16_f32 v13, v22, v23
	v_cvt_pk_bf16_f32 v14, v14, v15
	v_cvt_pk_bf16_f32 v15, v24, v25
	global_store_dwordx4 v36, v[12:15], s[22:23] offset:256 nt
	v_add_u32_e32 v20, s82, v36
	s_nop 0
	v_pk_mul_f32 v[12:13], v[140:141], v[18:19] op_sel_hi:[0,1]
	v_pk_mul_f32 v[14:15], v[140:141], v[16:17] op_sel_hi:[0,1]
	v_pk_mul_f32 v[16:17], v[140:141], v[10:11] op_sel_hi:[0,1]
	v_pk_mul_f32 v[10:11], v[140:141], v[8:9] op_sel_hi:[0,1]
	v_cvt_pk_bf16_f32 v8, v14, v15
	v_cvt_pk_bf16_f32 v9, v12, v13
	v_cvt_pk_bf16_f32 v10, v10, v11
	v_cvt_pk_bf16_f32 v11, v16, v17
	global_store_dwordx4 v20, v[8:11], s[22:23] nt
	s_nop 1
	v_pk_mul_f32 v[8:9], v[140:141], v[2:3] op_sel_hi:[0,1]
	v_pk_mul_f32 v[2:3], v[140:141], v[0:1] op_sel_hi:[0,1]
	v_cvt_pk_bf16_f32 v0, v4, v5
	v_cvt_pk_bf16_f32 v1, v6, v7
	v_cvt_pk_bf16_f32 v2, v2, v3
	v_cvt_pk_bf16_f32 v3, v8, v9
	global_store_dwordx4 v20, v[0:3], s[22:23] offset:256 nt
	s_cbranch_vccnz .LBB0_1074
	s_andn2_b64 vcc, exec, s[14:15]
	s_cbranch_vccnz .LBB0_1073
	s_barrier
	s_branch .LBB0_1073
